# y-pass k-loop: priority raise moved ahead of the LDS fragment reads of each MFMA cluster
# baseline (speedup 1.0000x reference)
; #define LAS __attribute__((address_space(3)))
; template <bool WIDE = false>
; DI void gemm_core(f32x4 (&acc)[4][4], const GOp& g, LAS char* lds, const int tidx, const bool have_first, const bool has_next, const GOp& gn, const bool fw16 = false) {
;     ...
; #pragma unroll
;         for (int ks = 0; ks < 2; ++ks) {
;             bf16x8 af[4], bfr[4];
; #pragma unroll
;             for (int i = 0; i < 4; ++i) af[i] = *(LAS bf16x8*)(st + aoff + i * 2048 + (sw ^ (ks * 64)));
; #pragma unroll
;             for (int i = 0; i < 4; ++i) bfr[i] = *(LAS bf16x8*)(st + boff + i * 2048 + (sw ^ (ks * 64)));
;             __builtin_amdgcn_s_setprio(1);
; #pragma unroll
;             for (int mi = 0; mi < 4; ++mi)
; #pragma unroll
;                 for (int ni = 0; ni < 4; ++ni) acc[mi][ni] = __builtin_amdgcn_mfma_f32_16x16x32_bf16(bfr[ni], af[mi], acc[mi][ni], 0, 0, 0);
;             __builtin_amdgcn_s_setprio(0);
;         }
.LBB0_268:
	s_and_b32 s4, s33, 0x8000
	v_add_u32_e32 v112, s4, v184
	v_or_b32_e32 v113, s4, v185
	s_setprio 1
	v_add_u32_e32 v119, v112, v182
	ds_read_b128 v[120:123], v119
	ds_read_b128 v[124:127], v119 offset:2048
	ds_read_b128 v[128:131], v119 offset:4096
	ds_read_b128 v[132:135], v119 offset:6144
	v_add_u32_e32 v119, v113, v182
	ds_read_b128 v[136:139], v119 offset:16384
	ds_read_b128 v[140:143], v119 offset:18432
	ds_read_b128 v[144:147], v119 offset:20480
	ds_read_b128 v[220:223], v119 offset:22528
	s_waitcnt lgkmcnt(0)
	v_mfma_f32_16x16x32_bf16 v[80:83], v[136:139], v[120:123], v[80:83]
	v_mfma_f32_16x16x32_bf16 v[76:79], v[140:143], v[120:123], v[76:79]
	v_mfma_f32_16x16x32_bf16 v[72:75], v[144:147], v[120:123], v[72:75]
	v_mfma_f32_16x16x32_bf16 v[68:71], v[220:223], v[120:123], v[68:71]
	v_mfma_f32_16x16x32_bf16 v[64:67], v[136:139], v[124:127], v[64:67]
	v_mfma_f32_16x16x32_bf16 v[60:63], v[140:143], v[124:127], v[60:63]
	v_mfma_f32_16x16x32_bf16 v[56:59], v[144:147], v[124:127], v[56:59]
	v_mfma_f32_16x16x32_bf16 v[52:55], v[220:223], v[124:127], v[52:55]
	v_mfma_f32_16x16x32_bf16 v[48:51], v[136:139], v[128:131], v[48:51]
	v_mfma_f32_16x16x32_bf16 v[44:47], v[140:143], v[128:131], v[44:47]
	v_mfma_f32_16x16x32_bf16 v[40:43], v[144:147], v[128:131], v[40:43]
	v_mfma_f32_16x16x32_bf16 v[36:39], v[220:223], v[128:131], v[36:39]
	v_mfma_f32_16x16x32_bf16 v[32:35], v[136:139], v[132:135], v[32:35]
	v_mfma_f32_16x16x32_bf16 v[28:31], v[140:143], v[132:135], v[28:31]
	v_mfma_f32_16x16x32_bf16 v[8:11], v[144:147], v[132:135], v[8:11]
	v_mfma_f32_16x16x32_bf16 v[4:7], v[220:223], v[132:135], v[4:7]
	s_setprio 0
	v_add_u32_e32 v112, v112, v186
	ds_read_b128 v[120:123], v112
	ds_read_b128 v[124:127], v112 offset:2048
	ds_read_b128 v[128:131], v112 offset:4096
	ds_read_b128 v[132:135], v112 offset:6144
	v_add_u32_e32 v112, v113, v186
	s_setprio 1
	ds_read_b128 v[136:139], v112 offset:16384
	ds_read_b128 v[140:143], v112 offset:18432
	ds_read_b128 v[144:147], v112 offset:20480
	ds_read_b128 v[220:223], v112 offset:22528
	s_waitcnt lgkmcnt(0)
	v_mfma_f32_16x16x32_bf16 v[80:83], v[136:139], v[120:123], v[80:83]
	v_mfma_f32_16x16x32_bf16 v[76:79], v[140:143], v[120:123], v[76:79]
	v_mfma_f32_16x16x32_bf16 v[72:75], v[144:147], v[120:123], v[72:75]
	v_mfma_f32_16x16x32_bf16 v[68:71], v[220:223], v[120:123], v[68:71]
	v_mfma_f32_16x16x32_bf16 v[64:67], v[136:139], v[124:127], v[64:67]
	v_mfma_f32_16x16x32_bf16 v[60:63], v[140:143], v[124:127], v[60:63]
	v_mfma_f32_16x16x32_bf16 v[56:59], v[144:147], v[124:127], v[56:59]
	v_mfma_f32_16x16x32_bf16 v[52:55], v[220:223], v[124:127], v[52:55]
	v_mfma_f32_16x16x32_bf16 v[48:51], v[136:139], v[128:131], v[48:51]
	v_mfma_f32_16x16x32_bf16 v[44:47], v[140:143], v[128:131], v[44:47]
	v_mfma_f32_16x16x32_bf16 v[40:43], v[144:147], v[128:131], v[40:43]
	v_mfma_f32_16x16x32_bf16 v[36:39], v[220:223], v[128:131], v[36:39]
	v_mfma_f32_16x16x32_bf16 v[32:35], v[136:139], v[132:135], v[32:35]
	v_mfma_f32_16x16x32_bf16 v[28:31], v[140:143], v[132:135], v[28:31]
	v_mfma_f32_16x16x32_bf16 v[8:11], v[144:147], v[132:135], v[8:11]
	v_mfma_f32_16x16x32_bf16 v[4:7], v[220:223], v[132:135], v[4:7]
	s_setprio 0
	s_add_i32 s33, s33, 0x8000
	s_cmp_eq_u32 s34, s56
	s_cbranch_scc1 .LBB0_270
	s_mov_b32 s4, s56
	s_branch .LBB0_260
